# local barriers v3: L1 invalidate issued before the store drain (overlapped), slot-based sync
# baseline (speedup 1.0000x reference)
.LBB0_262:
	s_cmp_gt_i32 s69, 3
	s_cselect_b64 s[0:1], -1, 0
	s_and_b64 s[2:3], s[4:5], s[0:1]
	s_andn2_b64 vcc, exec, s[2:3]
	s_cbranch_vccnz .LBB0_316
	buffer_inv sc1
	s_waitcnt vmcnt(0)
	s_waitcnt vmcnt(0) lgkmcnt(0)
	s_barrier
	v_mov_b32_e32 v0, 0x20040
	ds_read_b32 v2, v0
	ds_read_b32 v3, v0 offset:16
	ds_read_b32 v5, v0 offset:8
	s_lshl_b32 s2, s33, 7
	s_add_u32 s2, s2, 0x3600
	v_lshl_add_u32 v0, v199, 2, s2
	v_mov_b32_e32 v6, 1
	s_waitcnt lgkmcnt(0)
	v_cmp_eq_u32_e32 vcc, 0, v3
	s_cbranch_vccnz .Lxl_orig_2
	v_cmp_lt_u32_e32 vcc, 32, v2
	s_cbranch_vccnz .Lxl_orig_2
	v_lshl_add_u32 v1, v5, 2, s2
	v_cmp_lt_u32_e32 vcc, v199, v2
	s_and_saveexec_b64 s[4:5], vcc
	s_cbranch_execz .LBB0_315
	v_cmp_eq_u32_e32 vcc, 0, v199
	s_and_saveexec_b64 s[2:3], vcc
	global_store_dword v1, v6, s[92:93]
	s_mov_b64 exec, s[2:3]
	s_mov_b32 s2, 0x20000

.LBB0_363:
	s_cmp_gt_i32 s69, 4
	s_cselect_b64 s[0:1], -1, 0
	s_and_b64 s[2:3], s[8:9], s[0:1]
	s_andn2_b64 vcc, exec, s[2:3]
	s_cbranch_vccnz .LBB0_417
	buffer_inv sc1
	s_waitcnt vmcnt(0)
	s_waitcnt vmcnt(0) lgkmcnt(0)
	s_barrier
	v_mov_b32_e32 v0, 0x20040
	ds_read_b32 v2, v0
	ds_read_b32 v3, v0 offset:16
	ds_read_b32 v5, v0 offset:8
	s_lshl_b32 s2, s33, 7
	s_add_u32 s2, s2, 0x3600
	v_lshl_add_u32 v0, v199, 2, s2
	v_mov_b32_e32 v6, 2
	s_waitcnt lgkmcnt(0)
	v_cmp_eq_u32_e32 vcc, 0, v3
	s_cbranch_vccnz .Lxl_orig_3
	v_cmp_lt_u32_e32 vcc, 32, v2
	s_cbranch_vccnz .Lxl_orig_3
	v_lshl_add_u32 v1, v5, 2, s2
	v_cmp_lt_u32_e32 vcc, v199, v2
	s_and_saveexec_b64 s[4:5], vcc
	s_cbranch_execz .LBB0_416
	v_cmp_eq_u32_e32 vcc, 0, v199
	s_and_saveexec_b64 s[2:3], vcc
	global_store_dword v1, v6, s[92:93]
	s_mov_b64 exec, s[2:3]
	s_mov_b32 s2, 0x20000

.LBB0_1502:
	s_cmp_gt_i32 s69, 7
	s_cselect_b64 s[2:3], -1, 0
	s_and_b64 s[0:1], s[0:1], s[2:3]
	s_andn2_b64 vcc, exec, s[0:1]
	s_cbranch_vccnz .LBB0_1556
	buffer_inv sc1
	s_waitcnt vmcnt(0)
	s_waitcnt vmcnt(0) lgkmcnt(0)
	s_barrier
	v_mov_b32_e32 v0, 0x20040
	ds_read_b32 v2, v0
	ds_read_b32 v3, v0 offset:16
	ds_read_b32 v5, v0 offset:8
	s_lshl_b32 s4, s33, 7
	s_add_u32 s4, s4, 0x3600
	v_lshl_add_u32 v0, v199, 2, s4
	v_mov_b32_e32 v6, 3
	s_waitcnt lgkmcnt(0)
	v_cmp_eq_u32_e32 vcc, 0, v3
	s_cbranch_vccnz .Lxl_orig_6
	v_cmp_lt_u32_e32 vcc, 32, v2
	s_cbranch_vccnz .Lxl_orig_6
	v_lshl_add_u32 v1, v5, 2, s4
	v_cmp_lt_u32_e32 vcc, v199, v2
	s_and_saveexec_b64 s[0:1], vcc
	s_cbranch_execz .LBB0_1555
	v_cmp_eq_u32_e32 vcc, 0, v199
	s_and_saveexec_b64 s[4:5], vcc
	global_store_dword v1, v6, s[92:93]
	s_mov_b64 exec, s[4:5]
	s_mov_b32 s4, 0x20000

.LBB0_1599:
	s_cmp_gt_i32 s69, 8
	s_cselect_b64 s[2:3], -1, 0
	s_and_b64 s[0:1], s[0:1], s[2:3]
	v_readlane_b32 s60, v255, 20
	s_andn2_b64 vcc, exec, s[0:1]
	v_readlane_b32 s61, v255, 21
	s_cbranch_vccnz .LBB0_1653
	buffer_inv sc1
	s_waitcnt vmcnt(0)
	s_waitcnt vmcnt(0) lgkmcnt(0)
	s_barrier
	v_mov_b32_e32 v0, 0x20040
	ds_read_b32 v2, v0
	ds_read_b32 v3, v0 offset:16
	ds_read_b32 v5, v0 offset:8
	s_lshl_b32 s4, s33, 7
	s_add_u32 s4, s4, 0x3600
	v_lshl_add_u32 v0, v199, 2, s4
	v_mov_b32_e32 v6, 4
	s_waitcnt lgkmcnt(0)
	v_cmp_eq_u32_e32 vcc, 0, v3
	s_cbranch_vccnz .Lxl_orig_7
	v_cmp_lt_u32_e32 vcc, 32, v2
	s_cbranch_vccnz .Lxl_orig_7
	v_lshl_add_u32 v1, v5, 2, s4
	v_cmp_lt_u32_e32 vcc, v199, v2
	s_and_saveexec_b64 s[0:1], vcc
	s_cbranch_execz .LBB0_1652
	v_cmp_eq_u32_e32 vcc, 0, v199
	s_and_saveexec_b64 s[4:5], vcc
	global_store_dword v1, v6, s[92:93]
	s_mov_b64 exec, s[4:5]
	s_mov_b32 s4, 0x20000

.LBB0_1710:
	s_cmp_gt_i32 s69, 9
	s_cselect_b64 s[0:1], -1, 0
	s_and_b64 s[2:3], s[6:7], s[0:1]
	s_andn2_b64 vcc, exec, s[2:3]
	s_cbranch_vccnz .LBB0_1764
	buffer_inv sc1
	s_waitcnt vmcnt(0)
	s_waitcnt vmcnt(0) lgkmcnt(0)
	s_barrier
	v_mov_b32_e32 v0, 0x20040
	ds_read_b32 v2, v0
	ds_read_b32 v3, v0 offset:16
	ds_read_b32 v5, v0 offset:8
	s_lshl_b32 s4, s33, 7
	s_add_u32 s4, s4, 0x3600
	v_lshl_add_u32 v0, v199, 2, s4
	v_mov_b32_e32 v6, 5
	s_waitcnt lgkmcnt(0)
	v_cmp_eq_u32_e32 vcc, 0, v3
	s_cbranch_vccnz .Lxl_orig_8
	v_cmp_lt_u32_e32 vcc, 32, v2
	s_cbranch_vccnz .Lxl_orig_8
	v_lshl_add_u32 v1, v5, 2, s4
	v_cmp_lt_u32_e32 vcc, v199, v2
	s_and_saveexec_b64 s[2:3], vcc
	s_cbranch_execz .LBB0_1763
	v_cmp_eq_u32_e32 vcc, 0, v199
	s_and_saveexec_b64 s[4:5], vcc
	global_store_dword v1, v6, s[92:93]
	s_mov_b64 exec, s[4:5]
	s_mov_b32 s4, 0x20000
